# diff fast path: next iteration DMA sources, m0 values and LDS read addresses precomputed in the MFMA shadow; own loop-back edge
# speedup vs baseline: 1.0289x; 1.0185x over previous
; #define MFMA(a, b, c) __builtin_amdgcn_mfma_f32_32x32x16_bf16((a), (b), (c), 0, 0, 0)
; DI float fexp2(float x) { return __builtin_amdgcn_exp2f(x); }
; DI void diff_pass(const bf16_t* __restrict__ qrow  , const bf16_t* __restrict__ kg, const bf16_t* __restrict__ vg,
;                   int nkt, int q0, float negM2, f32x16 (&O)[4], float& lsum, char* lds) {
;     ...
;         if (kt * 64 <= q0 + 31) {
;             f32x16 Sx[2];
;             {
;                 bf16x8 kf[2][4];
; #pragma unroll
;                 for (int kb = 0; kb < 2; ++kb)
; #pragma unroll
;                     for (int ks = 0; ks < 4; ++ks) kf[kb][ks] = *(const bf16x8*)(st + (32 * kb + l31) * 128 + (((2 * ks + h) ^ f) << 4));
;                 __builtin_amdgcn_sched_barrier(0);
; #pragma unroll
;                 for (int ks = 0; ks < 4; ++ks)
; #pragma unroll
;                     for (int kb = 0; kb < 2; ++kb) Sx[kb] = ks == 0 ? MFMA(kf[kb][0], qf[0], minit) : MFMA(kf[kb][ks], qf[ks], Sx[kb]);
;             }
;             if (kt * 64 + 63 > q0) {
; #pragma unroll
;                 for (int kb = 0; kb < 2; ++kb)
; #pragma unroll
;                     for (int i = 0; i < 16; ++i) {
;                         float p = fexp2(Sx[kb][i]);
;                         const int key = kt * 64 + 32 * kb + (i & 3) + 8 * (i >> 2) + 4 * h;
;                         if (key > qpos) p = 0.f;
;                         lsum += p; Sx[kb][i] = p;
;                     }
.Ldf_slow_entry:
	v_cmp_le_i32_e32 vcc, s55, v171
	s_and_saveexec_b64 s[28:29], vcc
	s_cbranch_execz .LBB0_87
	s_cmp_eq_u32 s30, 1
	s_cselect_b32 s30, 0, 0x6000
	v_or_b32_e32 v0, s30, v188
	v_add_u32_e32 v195, v0, v189
	v_add_u32_e32 v194, v0, v190
	v_add_u32_e32 v193, v0, v191
	v_add_u32_e32 v0, v0, v192
	s_add_i32 s30, s55, 63
	v_cmp_le_i32_e32 vcc, s30, v148
	s_cbranch_vccnz .Ldf_fast
	ds_read_b128 v[2:5], v195
	ds_read_b128 v[6:9], v195 offset:4096
	ds_read_b128 v[10:13], v194
	ds_read_b128 v[196:199], v194 offset:4096
	ds_read_b128 v[200:203], v193
	ds_read_b128 v[204:207], v193 offset:4096
	ds_read_b128 v[208:211], v0
	ds_read_b128 v[212:215], v0 offset:4096
	s_waitcnt lgkmcnt(0)
	v_mfma_f32_32x32x16_bf16 v[96:111], v[2:5], v[140:143], v[16:31]
	s_add_i32 s30, s55, 63
	v_cmp_le_i32_e32 vcc, s30, v148
	v_mfma_f32_32x32x16_bf16 v[112:127], v[6:9], v[140:143], v[16:31]
	v_mfma_f32_32x32x16_bf16 v[96:111], v[10:13], v[136:139], v[96:111]
	v_mfma_f32_32x32x16_bf16 v[112:127], v[196:199], v[136:139], v[112:127]
	v_mfma_f32_32x32x16_bf16 v[96:111], v[200:203], v[132:135], v[96:111]
	v_mfma_f32_32x32x16_bf16 v[112:127], v[204:207], v[132:135], v[112:127]
	v_mfma_f32_32x32x16_bf16 v[96:111], v[208:211], v[128:131], v[96:111]
	v_mfma_f32_32x32x16_bf16 v[112:127], v[212:215], v[128:131], v[112:127]
	s_nop 10
	v_exp_f32_e32 v2, v96
	v_exp_f32_e32 v4, v97
	v_exp_f32_e32 v6, v98
	v_exp_f32_e32 v8, v99
	v_exp_f32_e32 v10, v100
	v_exp_f32_e32 v12, v101
	v_exp_f32_e32 v14, v102
	v_exp_f32_e32 v3, v112
	v_exp_f32_e32 v5, v113
	v_exp_f32_e32 v7, v114
	v_exp_f32_e32 v9, v115
	v_exp_f32_e32 v11, v116
	v_exp_f32_e32 v13, v117
	v_exp_f32_e32 v15, v118
	v_exp_f32_e32 v96, v103
	v_exp_f32_e32 v97, v119
	v_exp_f32_e32 v100, v104
	v_exp_f32_e32 v101, v120
	v_exp_f32_e32 v104, v105
	v_exp_f32_e32 v105, v121
	v_exp_f32_e32 v98, v106
	v_exp_f32_e32 v99, v122
	v_exp_f32_e32 v102, v107
	v_exp_f32_e32 v103, v123
	v_exp_f32_e32 v106, v108
	v_exp_f32_e32 v107, v124
	v_exp_f32_e32 v108, v109
	v_exp_f32_e32 v109, v125
	v_exp_f32_e32 v112, v110
	v_exp_f32_e32 v113, v126
	v_exp_f32_e32 v110, v111
	v_exp_f32_e32 v111, v127
	s_and_saveexec_b64 s[30:31], vcc
	s_xor_b64 s[30:31], exec, s[30:31]
	s_cbranch_execz .LBB0_91
	v_pk_add_f32 v[114:115], v[2:3], 0 op_sel_hi:[1,0]
	s_nop 0
	v_pk_add_f32 v[114:115], v[4:5], v[114:115]
	s_nop 0
	v_pk_add_f32 v[114:115], v[6:7], v[114:115]
	s_nop 0
	v_pk_add_f32 v[114:115], v[8:9], v[114:115]
	s_nop 0
	v_pk_add_f32 v[114:115], v[10:11], v[114:115]
	s_nop 0
	v_pk_add_f32 v[114:115], v[12:13], v[114:115]
	s_nop 0
	v_pk_add_f32 v[114:115], v[14:15], v[114:115]
	s_nop 0
	v_pk_add_f32 v[114:115], v[96:97], v[114:115]
	s_nop 0
	v_pk_add_f32 v[114:115], v[100:101], v[114:115]
	s_nop 0
	v_pk_add_f32 v[114:115], v[104:105], v[114:115]
	s_nop 0
	v_pk_add_f32 v[114:115], v[98:99], v[114:115]
	s_nop 0
	v_pk_add_f32 v[114:115], v[102:103], v[114:115]
	s_nop 0
	v_pk_add_f32 v[114:115], v[106:107], v[114:115]
	s_nop 0
	v_pk_add_f32 v[114:115], v[108:109], v[114:115]
	s_nop 0
	v_pk_add_f32 v[114:115], v[112:113], v[114:115]
	s_nop 0
	v_pk_add_f32 v[114:115], v[110:111], v[114:115]
	s_nop 0
	v_add_f32_e32 v114, v114, v115
	v_add_f32_e32 v186, v186, v114

; DI void diff_pass(const bf16_t* __restrict__ qrow  , const bf16_t* __restrict__ kg, const bf16_t* __restrict__ vg,
;                   int nkt, int q0, float negM2, f32x16 (&O)[4], float& lsum, char* lds) {
;     ...
;     for (int kt = 0; kt < nkt; ++kt) {
;         char* st = lds + (kt & 1) * 24576;
;         if (kt + 1 < nkt) {
;             char* st2 = lds + ((kt + 1) & 1) * 24576 + wb;
;             __builtin_amdgcn_global_load_lds((const unsigned*)(kgs + (size_t)(kt + 1) * 64 * 512), (lds_ptr_t)(st2), 16, 0, 0);
;             __builtin_amdgcn_global_load_lds((const unsigned*)(vgs + (kt + 1) * 64), (lds_ptr_t)(st2 + 8192), 16, 0, 0);
;             __builtin_amdgcn_global_load_lds((const unsigned*)(vgs + (size_t)64 * kS + (kt + 1) * 64), (lds_ptr_t)(st2 + 16384), 16, 0, 0);
;         }
;         __builtin_amdgcn_sched_barrier(0);
;         if (kt * 64 <= q0 + 31) {
;             f32x16 Sx[2];
;             {
;                 bf16x8 kf[2][4];
; #pragma unroll
;                 for (int kb = 0; kb < 2; ++kb)
; #pragma unroll
;                     for (int ks = 0; ks < 4; ++ks) kf[kb][ks] = *(const bf16x8*)(st + (32 * kb + l31) * 128 + (((2 * ks + h) ^ f) << 4));
;                 __builtin_amdgcn_sched_barrier(0);
; #pragma unroll
;                 for (int ks = 0; ks < 4; ++ks)
; #pragma unroll
;                     for (int kb = 0; kb < 2; ++kb) Sx[kb] = ks == 0 ? MFMA(kf[kb][0], qf[0], minit) : MFMA(kf[kb][ks], qf[ks], Sx[kb]);
;             }
;             if (kt * 64 + 63 > q0) {
; #pragma unroll
;                 for (int kb = 0; kb < 2; ++kb)
; #pragma unroll
;                     for (int i = 0; i < 16; ++i) {
;                         float p = fexp2(Sx[kb][i]);
;                         const int key = kt * 64 + 32 * kb + (i & 3) + 8 * (i >> 2) + 4 * h;
;                         if (key > qpos) p = 0.f;
;                         lsum += p; Sx[kb][i] = p;
;                     }
;             } else {
;                 float l0 = 0.f, l1 = 0.f;
; #pragma unroll
;                 for (int i = 0; i < 16; ++i) { const float p0 = fexp2(Sx[0][i]), p1 = fexp2(Sx[1][i]); l0 += p0; l1 += p1; Sx[0][i] = p0; Sx[1][i] = p1; }
;                 lsum += l0 + l1;
;             }
;             bf16x8 pf[4];
;             pf[0] = pack8(Sx[0], 0); pf[1] = pack8(Sx[0], 1); pf[2] = pack8(Sx[1], 0); pf[3] = pack8(Sx[1], 1);
;             {
.Ldf_fast:
	ds_read_b128 v[2:5], v195
	ds_read_b128 v[10:13], v194
	ds_read_b128 v[200:203], v193
	ds_read_b128 v[208:211], v0
	ds_read_b128 v[6:9], v195 offset:4096
	ds_read_b128 v[196:199], v194 offset:4096
	ds_read_b128 v[204:207], v193 offset:4096
	ds_read_b128 v[212:215], v0 offset:4096
	v_mov_b32_e32 v14, 0
	v_mov_b32_e32 v15, 0
	s_waitcnt lgkmcnt(7)
	v_mfma_f32_32x32x16_bf16 v[96:111], v[2:5], v[140:143], v[16:31]
	s_waitcnt lgkmcnt(6)
	v_mfma_f32_32x32x16_bf16 v[96:111], v[10:13], v[136:139], v[96:111]
	s_waitcnt lgkmcnt(5)
	v_mfma_f32_32x32x16_bf16 v[96:111], v[200:203], v[132:135], v[96:111]
	s_waitcnt lgkmcnt(4)
	v_mfma_f32_32x32x16_bf16 v[96:111], v[208:211], v[128:131], v[96:111]
	s_waitcnt lgkmcnt(3)
	v_mfma_f32_32x32x16_bf16 v[112:127], v[6:9], v[140:143], v[16:31]
	ds_read_b128 v[2:5], v195 offset:8192
	ds_read_b128 v[10:13], v195 offset:12288
	s_waitcnt lgkmcnt(4)
	v_mfma_f32_32x32x16_bf16 v[112:127], v[196:199], v[136:139], v[112:127]
	ds_read_b128 v[200:203], v195 offset:16384
	ds_read_b128 v[208:211], v195 offset:20480
	s_nop 3
	v_exp_f32_e32 v96, v96
	v_exp_f32_e32 v97, v97
	v_add_f32_e32 v14, v14, v96
	v_add_f32_e32 v14, v14, v97
	s_waitcnt lgkmcnt(5)
	v_mfma_f32_32x32x16_bf16 v[112:127], v[204:207], v[132:135], v[112:127]
	v_exp_f32_e32 v98, v98
	v_exp_f32_e32 v99, v99
	v_add_f32_e32 v14, v14, v98
	v_add_f32_e32 v14, v14, v99
	s_waitcnt lgkmcnt(4)
	v_mfma_f32_32x32x16_bf16 v[112:127], v[212:215], v[128:131], v[112:127]
	v_exp_f32_e32 v100, v100
	v_exp_f32_e32 v101, v101
	v_add_f32_e32 v14, v14, v100
	v_add_f32_e32 v14, v14, v101
	v_exp_f32_e32 v102, v102
	v_exp_f32_e32 v103, v103
	v_add_f32_e32 v14, v14, v102
	v_add_f32_e32 v14, v14, v103
	v_cvt_pk_bf16_f32 v96, v96, v97
	v_cvt_pk_bf16_f32 v97, v98, v99
	v_cvt_pk_bf16_f32 v98, v100, v101
	v_cvt_pk_bf16_f32 v99, v102, v103
	s_waitcnt lgkmcnt(3)
	s_nop 0
	v_mfma_f32_32x32x16_bf16 v[80:95], v[2:5], v[96:99], v[80:95]
	ds_read_b128 v[6:9], v194 offset:8192
	ds_read_b128 v[196:199], v194 offset:12288
	ds_read_b128 v[204:207], v194 offset:16384
	ds_read_b128 v[212:215], v194 offset:20480
	v_exp_f32_e32 v104, v104
	v_exp_f32_e32 v105, v105
	v_add_f32_e32 v14, v14, v104
	v_add_f32_e32 v14, v14, v105
	s_waitcnt lgkmcnt(6)
	v_mfma_f32_32x32x16_bf16 v[64:79], v[10:13], v[96:99], v[64:79]
	ds_read_b128 v[2:5], v193 offset:8192
	v_exp_f32_e32 v106, v106
	v_exp_f32_e32 v107, v107
	v_add_f32_e32 v14, v14, v106
	v_add_f32_e32 v14, v14, v107
	s_waitcnt lgkmcnt(6)
	v_mfma_f32_32x32x16_bf16 v[48:63], v[200:203], v[96:99], v[48:63]
	ds_read_b128 v[10:13], v193 offset:12288
	v_exp_f32_e32 v108, v108
	v_exp_f32_e32 v109, v109
	v_add_f32_e32 v14, v14, v108
	v_add_f32_e32 v14, v14, v109
	s_waitcnt lgkmcnt(6)
	v_mfma_f32_32x32x16_bf16 v[32:47], v[208:211], v[96:99], v[32:47]
	ds_read_b128 v[200:203], v193 offset:16384
	v_exp_f32_e32 v110, v110
	v_exp_f32_e32 v111, v111
	v_add_f32_e32 v14, v14, v110
	v_add_f32_e32 v14, v14, v111
	v_cvt_pk_bf16_f32 v104, v104, v105
	v_cvt_pk_bf16_f32 v105, v106, v107
	v_cvt_pk_bf16_f32 v106, v108, v109
	v_cvt_pk_bf16_f32 v107, v110, v111
	s_waitcnt lgkmcnt(6)
	s_nop 0
	v_mfma_f32_32x32x16_bf16 v[80:95], v[6:9], v[104:107], v[80:95]
	ds_read_b128 v[208:211], v193 offset:20480
	v_exp_f32_e32 v112, v112
	v_exp_f32_e32 v113, v113
	v_add_f32_e32 v15, v15, v112
	v_add_f32_e32 v15, v15, v113
	s_waitcnt lgkmcnt(6)
	v_mfma_f32_32x32x16_bf16 v[64:79], v[196:199], v[104:107], v[64:79]
	ds_read_b128 v[6:9], v0 offset:8192
	v_exp_f32_e32 v114, v114
	v_exp_f32_e32 v115, v115
	v_add_f32_e32 v15, v15, v114
	v_add_f32_e32 v15, v15, v115
	s_waitcnt lgkmcnt(6)
	v_mfma_f32_32x32x16_bf16 v[48:63], v[204:207], v[104:107], v[48:63]
	ds_read_b128 v[196:199], v0 offset:12288
	v_exp_f32_e32 v116, v116
	v_exp_f32_e32 v117, v117
	v_add_f32_e32 v15, v15, v116
	v_add_f32_e32 v15, v15, v117
	s_waitcnt lgkmcnt(6)
	v_mfma_f32_32x32x16_bf16 v[32:47], v[212:215], v[104:107], v[32:47]
	ds_read_b128 v[204:207], v0 offset:16384
	v_exp_f32_e32 v118, v118
	v_exp_f32_e32 v119, v119
	v_add_f32_e32 v15, v15, v118
	v_add_f32_e32 v15, v15, v119
	v_cvt_pk_bf16_f32 v112, v112, v113
	v_cvt_pk_bf16_f32 v113, v114, v115
	v_cvt_pk_bf16_f32 v114, v116, v117
	v_cvt_pk_bf16_f32 v115, v118, v119
	s_waitcnt lgkmcnt(6)
	s_nop 0
	v_mfma_f32_32x32x16_bf16 v[80:95], v[2:5], v[112:115], v[80:95]
	ds_read_b128 v[212:215], v0 offset:20480
	s_and_b32 s0, 1, s54
	s_cselect_b32 s0, 0x6000, 0
	s_xor_b32 s1, s0, 0x6000
	v_or_b32_e32 v0, s0, v188
	v_readfirstlane_b32 s32, v187
	v_add_u32_e32 v195, v0, v189
	v_add_u32_e32 v194, v0, v190
	v_add_u32_e32 v193, v0, v191
	v_add_u32_e32 v0, v0, v192
	s_mov_b64 s[28:29], 0x10000
	v_lshl_add_u64 v[216:217], v[160:161], 0, v[158:159]
	v_lshl_add_u64 v[218:219], v[164:165], 0, v[158:159]
	v_lshl_add_u64 v[216:217], v[216:217], 0, s[28:29]
	s_mov_b64 s[28:29], 0x1b800100
	v_lshl_add_u64 v[220:221], v[218:219], 0, s[28:29]
	s_mov_b64 s[28:29], 0x1b900100
	v_lshl_add_u64 v[218:219], v[218:219], 0, s[28:29]
	v_exp_f32_e32 v120, v120
	v_exp_f32_e32 v121, v121
	v_add_f32_e32 v15, v15, v120
	v_add_f32_e32 v15, v15, v121
	s_waitcnt lgkmcnt(6)
	v_mfma_f32_32x32x16_bf16 v[64:79], v[10:13], v[112:115], v[64:79]
	v_exp_f32_e32 v122, v122
	v_exp_f32_e32 v123, v123
	v_add_f32_e32 v15, v15, v122
	v_add_f32_e32 v15, v15, v123
	s_waitcnt lgkmcnt(5)
	v_mfma_f32_32x32x16_bf16 v[48:63], v[200:203], v[112:115], v[48:63]
	v_exp_f32_e32 v124, v124
	v_exp_f32_e32 v125, v125
	v_add_f32_e32 v15, v15, v124
	v_add_f32_e32 v15, v15, v125
	s_waitcnt lgkmcnt(4)
	v_mfma_f32_32x32x16_bf16 v[32:47], v[208:211], v[112:115], v[32:47]
	v_exp_f32_e32 v126, v126
	v_exp_f32_e32 v127, v127
	v_add_f32_e32 v15, v15, v126
	v_add_f32_e32 v15, v15, v127
	v_cvt_pk_bf16_f32 v120, v120, v121
	v_cvt_pk_bf16_f32 v121, v122, v123
	v_cvt_pk_bf16_f32 v122, v124, v125
	v_cvt_pk_bf16_f32 v123, v126, v127
	v_add_f32_e32 v14, v14, v15
	s_waitcnt lgkmcnt(3)
	v_mfma_f32_32x32x16_bf16 v[80:95], v[6:9], v[120:123], v[80:95]
	v_add_f32_e32 v186, v186, v14
	s_waitcnt lgkmcnt(2)
	v_mfma_f32_32x32x16_bf16 v[64:79], v[196:199], v[120:123], v[64:79]
	s_waitcnt lgkmcnt(1)
	v_mfma_f32_32x32x16_bf16 v[48:63], v[204:207], v[120:123], v[48:63]
	s_waitcnt lgkmcnt(0)
	v_mfma_f32_32x32x16_bf16 v[32:47], v[212:215], v[120:123], v[32:47]
	s_waitcnt vmcnt(0)
	s_add_i32 s55, s55, 64
	s_add_i32 s54, s54, 1
	s_mov_b64 s[28:29], 0x10000
	v_lshl_add_u64 v[164:165], v[164:165], 0, s[18:19]
	s_cmp_eq_u32 s35, s55
	v_lshl_add_u64 v[160:161], v[160:161], 0, s[28:29]
	s_waitcnt lgkmcnt(0)
	s_barrier
	s_cbranch_scc1 .LBB0_93
	s_add_i32 s28, s1, s32
	s_mov_b32 m0, s28
	s_nop 0
	global_load_lds_dwordx4 v[216:217], off
	s_add_i32 s28, s28, 0x2000
	s_mov_b32 m0, s28
	s_nop 0
	global_load_lds_dwordx4 v[220:221], off
	s_add_i32 s28, s28, 0x2000
	s_mov_b32 m0, s28
	s_nop 0
	global_load_lds_dwordx4 v[218:219], off
	s_add_i32 s30, s55, 63
	v_cmp_le_i32_e32 vcc, s30, v148
	s_cbranch_vccnz .Ldf_fast
	s_and_b32 s30, 1, s54
	s_branch .Ldf_slow_entry
